# more rsqrt(x+eps) sequences simplified (19 additional sites)
# speedup vs baseline: 1.0090x; 1.0010x over previous
; __device__ __forceinline__ unsigned pk_bf16(float lo, float hi) { f32x2 v = {lo, hi}; bf16x2_t b = __builtin_convertvector(v, bf16x2_t); return __builtin_bit_cast(unsigned, b); }
;     __device__ __forceinline__ void operator()(const f32x4 (&acc)[2][2][4][2], const Unit& u, int wr, int wc, int fr, int fq) const {
;     ...
;                         const int row = row0 + ai * HALF + m * 16;
;                         const float rv = rsqrtf(rowss[row] * (1.0f / 1024.0f) + 1e-6f);
;                         const f32x4 v0 = (acc[ai][bj][m][0] * rv + bz0) * qsc, v1 = (acc[ai][bj][m][1] * rv + bz1) * qsc;
;                         if (isk) { float s2 = (v0[0] * v0[0] + v0[1] * v0[1]) + (v0[2] * v0[2] + v0[3] * v0[3]) + (v1[0] * v1[0] + v1[1] * v1[1]) + (v1[2] * v1[2] + v1[3] * v1[3]);
;                             s2 += __shfl_xor(s2, 16); s2 += __shfl_xor(s2, 32); kmx = fmaxf(kmx, s2); }
;                         u32x4 w; w.x = pk_bf16(v0[0], v0[1]); w.y = pk_bf16(v0[2], v0[3]); w.z = pk_bf16(v1[0], v1[1]); w.w = pk_bf16(v1[2], v1[3]);
;                         *(u32x4*)(base + (size_t)row * pitch) = w;
.LBB0_279:
	s_lshl_b64 s[4:5], s[42:43], 1
	s_add_u32 s1, s2, s4
	s_addc_u32 s4, s3, s5
	s_lshl_b32 s0, s0, 1
	s_add_u32 s0, s1, s0
	s_addc_u32 s1, s4, 0
	s_lshl_b32 s59, s91, 1
	s_add_u32 s0, s0, s59
	s_addc_u32 s1, s1, 0
	v_lshl_add_u64 v[120:121], v[164:165], 1, s[0:1]
	v_cvt_pk_bf16_f32 v171, v122, v123
	v_mad_i64_i32 v[122:123], s[0:1], s74, v162, 0
	v_cvt_pk_bf16_f32 v168, v168, v169
	v_cvt_pk_bf16_f32 v169, v124, v125
	v_cvt_pk_bf16_f32 v170, v126, v127
	v_lshl_add_u64 v[122:123], v[122:123], 1, v[120:121]
	global_store_dwordx4 v[122:123], v[168:171], off
	s_nop 0
	v_mov_b32_e32 v141, v140
	v_mov_b32_e32 v122, v140
	v_mov_b32_e32 v123, v140
	s_andn2_b64 vcc, exec, s[68:69]
	v_fmamk_f32 v124, v188, 0x3a800000, v227
	s_nop 1
	v_rsq_f32_e32 v124, v124
	v_cndmask_b32_e64 v125, 0, 1, s[68:69]
	v_cmp_ne_u32_e64 s[42:43], 1, v125
	v_pk_fma_f32 v[116:117], v[116:117], v[124:125], v[134:135] op_sel_hi:[1,0,1]
	v_pk_fma_f32 v[118:119], v[118:119], v[124:125], v[136:137] op_sel_hi:[1,0,1]
	v_pk_fma_f32 v[126:127], v[112:113], v[124:125], v[130:131] op_sel_hi:[1,0,1]
	v_pk_fma_f32 v[112:113], v[114:115], v[124:125], v[132:133] op_sel_hi:[1,0,1]
	v_pk_mul_f32 v[114:115], v[122:123], v[118:119]
	v_pk_mul_f32 v[118:119], v[140:141], v[116:117]
	v_pk_mul_f32 v[112:113], v[122:123], v[112:113]
	v_pk_mul_f32 v[116:117], v[140:141], v[126:127]
	s_cbranch_vccnz .LBB0_281
	v_pk_mul_f32 v[124:125], v[114:115], v[114:115]
	v_pk_mul_f32 v[126:127], v[118:119], v[118:119]
	s_nop 0
	v_pk_mov_b32 v[168:169], v[126:127], v[124:125] op_sel:[1,0]
	v_mov_b32_e32 v127, v125
	v_pk_add_f32 v[124:125], v[168:169], v[126:127]
	v_pk_mul_f32 v[126:127], v[112:113], v[112:113]
	v_pk_mul_f32 v[168:169], v[116:117], v[116:117]
	v_mov_b32_e32 v170, v126
	v_mov_b32_e32 v171, v168
	v_mov_b32_e32 v168, v127
	v_pk_add_f32 v[126:127], v[170:171], v[168:169]
	v_add_f32_e32 v124, v124, v125
	v_add_f32_e32 v124, v127, v124
	v_add_f32_e32 v124, v126, v124
	v_and_b32_e32 v126, 64, v230
	v_xor_b32_e32 v125, 16, v230
	v_add_u32_e32 v126, 64, v126
	v_cmp_lt_i32_e32 vcc, v125, v126
	s_nop 1
	v_cndmask_b32_e32 v125, v230, v125, vcc
	v_lshlrev_b32_e32 v125, 2, v125
	ds_bpermute_b32 v125, v125, v124
	s_waitcnt lgkmcnt(0)
	v_add_f32_e32 v124, v124, v125
	v_xor_b32_e32 v125, 32, v230
	v_cmp_lt_i32_e32 vcc, v125, v126
	s_nop 1
	v_cndmask_b32_e32 v125, v230, v125, vcc
	v_lshlrev_b32_e32 v125, 2, v125
	ds_bpermute_b32 v125, v125, v124
	s_waitcnt lgkmcnt(0)
	v_add_f32_e32 v124, v124, v125
	v_max_f32_e32 v125, v159, v159
	v_max_f32_e32 v159, v125, v124

; __device__ __forceinline__ unsigned pk_bf16(float lo, float hi) { f32x2 v = {lo, hi}; bf16x2_t b = __builtin_convertvector(v, bf16x2_t); return __builtin_bit_cast(unsigned, b); }
;     __device__ __forceinline__ void operator()(const f32x4 (&acc)[2][2][4][2], const Unit& u, int wr, int wc, int fr, int fq) const {
;     ...
;                         const int row = row0 + ai * HALF + m * 16;
;                         const float rv = rsqrtf(rowss[row] * (1.0f / 1024.0f) + 1e-6f);
;                         const f32x4 v0 = (acc[ai][bj][m][0] * rv + bz0) * qsc, v1 = (acc[ai][bj][m][1] * rv + bz1) * qsc;
;                         if (isk) { float s2 = (v0[0] * v0[0] + v0[1] * v0[1]) + (v0[2] * v0[2] + v0[3] * v0[3]) + (v1[0] * v1[0] + v1[1] * v1[1]) + (v1[2] * v1[2] + v1[3] * v1[3]);
;                             s2 += __shfl_xor(s2, 16); s2 += __shfl_xor(s2, 32); kmx = fmaxf(kmx, s2); }
;                         u32x4 w; w.x = pk_bf16(v0[0], v0[1]); w.y = pk_bf16(v0[2], v0[3]); w.z = pk_bf16(v1[0], v1[1]); w.w = pk_bf16(v1[2], v1[3]);
;                         *(u32x4*)(base + (size_t)row * pitch) = w;
.LBB0_283:
	v_cvt_pk_bf16_f32 v113, v104, v105
	v_mad_i64_i32 v[104:105], s[0:1], s74, v242, 0
	v_cvt_pk_bf16_f32 v110, v110, v111
	v_cvt_pk_bf16_f32 v111, v106, v107
	v_cvt_pk_bf16_f32 v112, v108, v109
	v_lshl_add_u64 v[104:105], v[104:105], 1, v[120:121]
	global_store_dwordx4 v[104:105], v[110:113], off
	s_nop 0
	s_and_b64 vcc, exec, s[42:43]
	v_fmamk_f32 v104, v190, 0x3a800000, v227
	s_nop 1
	v_rsq_f32_e32 v106, v104
	v_mov_b32_e32 v104, v140
	v_mov_b32_e32 v105, v140
	v_pk_fma_f32 v[100:101], v[100:101], v[106:107], v[134:135] op_sel_hi:[1,0,1]
	v_pk_fma_f32 v[102:103], v[102:103], v[106:107], v[136:137] op_sel_hi:[1,0,1]
	v_pk_fma_f32 v[108:109], v[96:97], v[106:107], v[130:131] op_sel_hi:[1,0,1]
	v_pk_fma_f32 v[96:97], v[98:99], v[106:107], v[132:133] op_sel_hi:[1,0,1]
	v_pk_mul_f32 v[98:99], v[104:105], v[102:103]
	v_pk_mul_f32 v[102:103], v[140:141], v[100:101]
	v_pk_mul_f32 v[96:97], v[104:105], v[96:97]
	v_pk_mul_f32 v[100:101], v[140:141], v[108:109]
	s_cbranch_vccnz .LBB0_285
	v_pk_mul_f32 v[106:107], v[98:99], v[98:99]
	v_pk_mul_f32 v[108:109], v[102:103], v[102:103]
	s_nop 0
	v_pk_mov_b32 v[110:111], v[108:109], v[106:107] op_sel:[1,0]
	v_mov_b32_e32 v109, v107
	v_pk_add_f32 v[106:107], v[110:111], v[108:109]
	v_pk_mul_f32 v[108:109], v[96:97], v[96:97]
	v_pk_mul_f32 v[110:111], v[100:101], v[100:101]
	v_mov_b32_e32 v112, v108
	v_mov_b32_e32 v113, v110
	v_mov_b32_e32 v110, v109
	v_pk_add_f32 v[108:109], v[112:113], v[110:111]
	v_add_f32_e32 v106, v106, v107
	v_add_f32_e32 v106, v109, v106
	v_add_f32_e32 v106, v108, v106
	v_and_b32_e32 v108, 64, v230
	v_xor_b32_e32 v107, 16, v230
	v_add_u32_e32 v108, 64, v108
	v_cmp_lt_i32_e32 vcc, v107, v108
	s_nop 1
	v_cndmask_b32_e32 v107, v230, v107, vcc
	v_lshlrev_b32_e32 v107, 2, v107
	ds_bpermute_b32 v107, v107, v106
	s_waitcnt lgkmcnt(0)
	v_add_f32_e32 v106, v106, v107
	v_xor_b32_e32 v107, 32, v230
	v_cmp_lt_i32_e32 vcc, v107, v108
	s_nop 1
	v_cndmask_b32_e32 v107, v230, v107, vcc
	v_lshlrev_b32_e32 v107, 2, v107
	ds_bpermute_b32 v107, v107, v106
	s_waitcnt lgkmcnt(0)
	v_add_f32_e32 v106, v106, v107
	v_max_f32_e32 v107, v159, v159
	v_max_f32_e32 v159, v107, v106

; __device__ __forceinline__ unsigned pk_bf16(float lo, float hi) { f32x2 v = {lo, hi}; bf16x2_t b = __builtin_convertvector(v, bf16x2_t); return __builtin_bit_cast(unsigned, b); }
;     __device__ __forceinline__ void operator()(const f32x4 (&acc)[2][2][4][2], const Unit& u, int wr, int wc, int fr, int fq) const {
;     ...
;                         const int row = row0 + ai * HALF + m * 16;
;                         const float rv = rsqrtf(rowss[row] * (1.0f / 1024.0f) + 1e-6f);
;                         const f32x4 v0 = (acc[ai][bj][m][0] * rv + bz0) * qsc, v1 = (acc[ai][bj][m][1] * rv + bz1) * qsc;
;                         if (isk) { float s2 = (v0[0] * v0[0] + v0[1] * v0[1]) + (v0[2] * v0[2] + v0[3] * v0[3]) + (v1[0] * v1[0] + v1[1] * v1[1]) + (v1[2] * v1[2] + v1[3] * v1[3]);
;                             s2 += __shfl_xor(s2, 16); s2 += __shfl_xor(s2, 32); kmx = fmaxf(kmx, s2); }
;                         u32x4 w; w.x = pk_bf16(v0[0], v0[1]); w.y = pk_bf16(v0[2], v0[3]); w.z = pk_bf16(v1[0], v1[1]); w.w = pk_bf16(v1[2], v1[3]);
;                         *(u32x4*)(base + (size_t)row * pitch) = w;
.LBB0_287:
	v_add_u32_e32 v96, 0x80, v162
	v_cvt_pk_bf16_f32 v101, v88, v89
	v_mad_i64_i32 v[88:89], s[0:1], s74, v96, 0
	v_cvt_pk_bf16_f32 v98, v94, v95
	v_cvt_pk_bf16_f32 v99, v90, v91
	v_cvt_pk_bf16_f32 v100, v92, v93
	v_lshl_add_u64 v[88:89], v[88:89], 1, v[120:121]
	global_store_dwordx4 v[88:89], v[98:101], off
	s_nop 0
	s_and_b64 vcc, exec, s[42:43]
	v_fmamk_f32 v88, v192, 0x3a800000, v227
	s_nop 1
	v_rsq_f32_e32 v90, v88
	v_mov_b32_e32 v88, v140
	v_mov_b32_e32 v89, v140
	v_pk_fma_f32 v[84:85], v[84:85], v[90:91], v[134:135] op_sel_hi:[1,0,1]
	v_pk_fma_f32 v[86:87], v[86:87], v[90:91], v[136:137] op_sel_hi:[1,0,1]
	v_pk_fma_f32 v[92:93], v[80:81], v[90:91], v[130:131] op_sel_hi:[1,0,1]
	v_pk_fma_f32 v[80:81], v[82:83], v[90:91], v[132:133] op_sel_hi:[1,0,1]
	v_pk_mul_f32 v[82:83], v[88:89], v[86:87]
	v_pk_mul_f32 v[86:87], v[140:141], v[84:85]
	v_pk_mul_f32 v[80:81], v[88:89], v[80:81]
	v_pk_mul_f32 v[84:85], v[140:141], v[92:93]
	s_cbranch_vccnz .LBB0_289
	v_pk_mul_f32 v[90:91], v[82:83], v[82:83]
	v_pk_mul_f32 v[92:93], v[86:87], v[86:87]
	s_nop 0
	v_pk_mov_b32 v[94:95], v[92:93], v[90:91] op_sel:[1,0]
	v_mov_b32_e32 v93, v91
	v_pk_add_f32 v[90:91], v[94:95], v[92:93]
	v_pk_mul_f32 v[92:93], v[80:81], v[80:81]
	v_pk_mul_f32 v[94:95], v[84:85], v[84:85]
	v_mov_b32_e32 v98, v92
	v_mov_b32_e32 v99, v94
	v_mov_b32_e32 v94, v93
	v_pk_add_f32 v[92:93], v[98:99], v[94:95]
	v_add_f32_e32 v90, v90, v91
	v_add_f32_e32 v90, v93, v90
	v_add_f32_e32 v90, v92, v90
	v_and_b32_e32 v92, 64, v230
	v_xor_b32_e32 v91, 16, v230
	v_add_u32_e32 v92, 64, v92
	v_cmp_lt_i32_e32 vcc, v91, v92
	s_nop 1
	v_cndmask_b32_e32 v91, v230, v91, vcc
	v_lshlrev_b32_e32 v91, 2, v91
	ds_bpermute_b32 v91, v91, v90
	s_waitcnt lgkmcnt(0)
	v_add_f32_e32 v90, v90, v91
	v_xor_b32_e32 v91, 32, v230
	v_cmp_lt_i32_e32 vcc, v91, v92
	s_nop 1
	v_cndmask_b32_e32 v91, v230, v91, vcc
	v_lshlrev_b32_e32 v91, 2, v91
	ds_bpermute_b32 v91, v91, v90
	s_waitcnt lgkmcnt(0)
	v_add_f32_e32 v90, v90, v91
	v_max_f32_e32 v91, v159, v159
	v_max_f32_e32 v159, v91, v90

; __device__ __forceinline__ unsigned pk_bf16(float lo, float hi) { f32x2 v = {lo, hi}; bf16x2_t b = __builtin_convertvector(v, bf16x2_t); return __builtin_bit_cast(unsigned, b); }
;     __device__ __forceinline__ void operator()(const f32x4 (&acc)[2][2][4][2], const Unit& u, int wr, int wc, int fr, int fq) const {
;     ...
;                         const int row = row0 + ai * HALF + m * 16;
;                         const float rv = rsqrtf(rowss[row] * (1.0f / 1024.0f) + 1e-6f);
;                         const f32x4 v0 = (acc[ai][bj][m][0] * rv + bz0) * qsc, v1 = (acc[ai][bj][m][1] * rv + bz1) * qsc;
;                         if (isk) { float s2 = (v0[0] * v0[0] + v0[1] * v0[1]) + (v0[2] * v0[2] + v0[3] * v0[3]) + (v1[0] * v1[0] + v1[1] * v1[1]) + (v1[2] * v1[2] + v1[3] * v1[3]);
;                             s2 += __shfl_xor(s2, 16); s2 += __shfl_xor(s2, 32); kmx = fmaxf(kmx, s2); }
;                         u32x4 w; w.x = pk_bf16(v0[0], v0[1]); w.y = pk_bf16(v0[2], v0[3]); w.z = pk_bf16(v1[0], v1[1]); w.w = pk_bf16(v1[2], v1[3]);
;                         *(u32x4*)(base + (size_t)row * pitch) = w;
.LBB0_291:
	v_add_u32_e32 v80, 0xa0, v162
	v_cvt_pk_bf16_f32 v85, v72, v73
	v_mad_i64_i32 v[72:73], s[0:1], s74, v80, 0
	v_cvt_pk_bf16_f32 v82, v78, v79
	v_cvt_pk_bf16_f32 v83, v74, v75
	v_cvt_pk_bf16_f32 v84, v76, v77
	v_lshl_add_u64 v[72:73], v[72:73], 1, v[120:121]
	global_store_dwordx4 v[72:73], v[82:85], off
	s_nop 0
	s_and_b64 vcc, exec, s[42:43]
	v_fmamk_f32 v72, v194, 0x3a800000, v227
	s_nop 1
	v_rsq_f32_e32 v74, v72
	v_mov_b32_e32 v72, v140
	v_mov_b32_e32 v73, v140
	v_pk_fma_f32 v[68:69], v[68:69], v[74:75], v[134:135] op_sel_hi:[1,0,1]
	v_pk_fma_f32 v[70:71], v[70:71], v[74:75], v[136:137] op_sel_hi:[1,0,1]
	v_pk_fma_f32 v[76:77], v[64:65], v[74:75], v[130:131] op_sel_hi:[1,0,1]
	v_pk_fma_f32 v[64:65], v[66:67], v[74:75], v[132:133] op_sel_hi:[1,0,1]
	v_pk_mul_f32 v[66:67], v[72:73], v[70:71]
	v_pk_mul_f32 v[70:71], v[140:141], v[68:69]
	v_pk_mul_f32 v[64:65], v[72:73], v[64:65]
	v_pk_mul_f32 v[68:69], v[140:141], v[76:77]
	s_cbranch_vccnz .LBB0_293
	v_pk_mul_f32 v[72:73], v[66:67], v[66:67]
	v_pk_mul_f32 v[74:75], v[70:71], v[70:71]
	s_nop 0
	v_pk_mov_b32 v[76:77], v[74:75], v[72:73] op_sel:[1,0]
	v_mov_b32_e32 v75, v73
	v_pk_add_f32 v[72:73], v[76:77], v[74:75]
	v_pk_mul_f32 v[74:75], v[64:65], v[64:65]
	v_pk_mul_f32 v[76:77], v[68:69], v[68:69]
	v_mov_b32_e32 v78, v74
	v_mov_b32_e32 v79, v76
	v_mov_b32_e32 v76, v75
	v_pk_add_f32 v[74:75], v[78:79], v[76:77]
	v_add_f32_e32 v72, v72, v73
	v_add_f32_e32 v72, v75, v72
	v_add_f32_e32 v72, v74, v72
	v_and_b32_e32 v74, 64, v230
	v_xor_b32_e32 v73, 16, v230
	v_add_u32_e32 v74, 64, v74
	v_cmp_lt_i32_e32 vcc, v73, v74
	s_nop 1
	v_cndmask_b32_e32 v73, v230, v73, vcc
	v_lshlrev_b32_e32 v73, 2, v73
	ds_bpermute_b32 v73, v73, v72
	s_waitcnt lgkmcnt(0)
	v_add_f32_e32 v72, v72, v73
	v_xor_b32_e32 v73, 32, v230
	v_cmp_lt_i32_e32 vcc, v73, v74
	s_nop 1
	v_cndmask_b32_e32 v73, v230, v73, vcc
	v_lshlrev_b32_e32 v73, 2, v73
	ds_bpermute_b32 v73, v73, v72
	s_waitcnt lgkmcnt(0)
	v_add_f32_e32 v72, v72, v73
	v_max_f32_e32 v73, v159, v159
	v_max_f32_e32 v159, v73, v72

; __device__ __forceinline__ unsigned pk_f16(float lo, float hi) { f32x2 v = {lo, hi}; f16x2_t h = __builtin_convertvector(v, f16x2_t); return __builtin_bit_cast(unsigned, h); }
; __device__ __forceinline__ f32x2 up_f16(unsigned w) { return __builtin_convertvector(__builtin_bit_cast(f16x2_t, w), f32x2); }
;     __device__ __forceinline__ void operator()(const f32x4 (&acc)[2][2][4][2], const Unit& u, int wr, int wc, int fr, int fq) const {
;     ...
;                 for (int m = 0; m < 4; ++m) { const size_t off = (size_t)(row0 + ai * HALF + m * 16) * 1024 + col0 + bj * HALF;
;                     float rc = 1.0f; if constexpr (GN) rc = rsqrtf(gss[2 * 32768 + row0 + ai * HALF + m * 16] * (1.0f / 384.0f) + 1e-6f);
;                     const u32x4 q = pq[ai][m];
;                     const f32x2 qa_ = up_f16(q.x), qb_ = up_f16(q.y), qc_ = up_f16(q.z), qd_ = up_f16(q.w);
;                     const f32x4 x0 = (f32x4){qa_[0], qa_[1], qb_[0], qb_[1]} + gv[0] * (acc[ai][bj][m][0] * rc),
;                                 x1 = (f32x4){qc_[0], qc_[1], qd_[0], qd_[1]} + gv[1] * (acc[ai][bj][m][1] * rc);
;                     { u32x4 wx; wx.x = pk_f16(x0[0], x0[1]); wx.y = pk_f16(x0[2], x0[3]); wx.z = pk_f16(x1[0], x1[1]); wx.w = pk_f16(x1[2], x1[3]); *(u32x4*)(out + off) = wx; }
.LBB0_806:
	s_lshl_b32 s1, s68, 8
	v_mov_b32_e32 v128, v237
	s_ashr_i32 s0, s69, 6
	s_or_b32 s1, s1, s29
	v_or_b32_e32 v140, 16, v186
	v_lshl_add_u32 v138, v128, 3, s1
	s_mul_hi_i32 s1, s0, 0x6000
	s_mulk_i32 s0, 0x6000
	s_add_u32 s0, s20, s0
	v_ashrrev_i32_e32 v139, 31, v138
	s_addc_u32 s1, s21, s1
	v_ashrrev_i32_e32 v141, 31, v140
	v_lshlrev_b64 v[208:209], 11, v[186:187]
	v_lshl_add_u64 v[190:191], v[138:139], 2, s[0:1]
	v_lshlrev_b64 v[246:247], 11, v[140:141]
	v_or_b32_e32 v140, 32, v186
	s_mov_b64 s[0:1], 0x48000
	v_ashrrev_i32_e32 v141, 31, v140
	v_lshl_add_u64 v[220:221], v[208:209], 0, s[0:1]
	s_mov_b64 s[0:1], 0x50000
	s_mov_b64 s[4:5], 0x40000
	v_lshlrev_b64 v[206:207], 1, v[138:139]
	v_lshlrev_b64 v[248:249], 11, v[140:141]
	v_or_b32_e32 v140, 48, v186
	v_lshl_add_u64 v[222:223], v[208:209], 0, s[0:1]
	s_mov_b64 s[0:1], 0x58000
	v_lshl_add_u64 v[218:219], v[208:209], 0, s[4:5]
	v_lshl_add_u64 v[138:139], s[96:97], 0, v[206:207]
	v_ashrrev_i32_e32 v141, 31, v140
	v_lshl_add_u64 v[216:217], v[208:209], 0, s[0:1]
	s_mov_b32 s0, 0x40000
	v_lshl_add_u64 v[192:193], v[138:139], 0, v[208:209]
	v_lshl_add_u64 v[196:197], v[138:139], 0, v[248:249]
	v_lshlrev_b64 v[224:225], 11, v[140:141]
	v_lshl_add_u64 v[200:201], v[138:139], 0, v[218:219]
	v_lshl_add_u64 v[204:205], v[138:139], 0, v[222:223]
	v_add_co_u32_e32 v188, vcc, s0, v188
	global_load_dwordx4 v[130:133], v[190:191], off offset:16
	global_load_dwordx4 v[134:137], v[190:191], off
	v_lshl_add_u64 v[194:195], v[138:139], 0, v[246:247]
	global_load_dwordx4 v[212:215], v[192:193], off
	global_load_dwordx4 v[242:245], v[194:195], off
	v_lshl_add_u64 v[198:199], v[138:139], 0, v[224:225]
	global_load_dwordx4 v[158:161], v[196:197], off
	global_load_dwordx4 v[154:157], v[198:199], off
	v_lshl_add_u64 v[202:203], v[138:139], 0, v[220:221]
	global_load_dwordx4 v[150:153], v[200:201], off
	global_load_dwordx4 v[146:149], v[202:203], off
	v_lshl_add_u64 v[210:211], v[138:139], 0, v[216:217]
	global_load_dwordx4 v[142:145], v[204:205], off
	global_load_dwordx4 v[138:141], v[210:211], off
	v_addc_co_u32_e32 v189, vcc, 0, v189, vcc
	global_load_dword v128, v[188:189], off
	global_load_dword v163, v[188:189], off offset:64
	global_load_dword v165, v[188:189], off offset:128
	global_load_dword v167, v[188:189], off offset:192
	global_load_dword v169, v[188:189], off offset:512
	global_load_dword v171, v[188:189], off offset:576
	global_load_dword v173, v[188:189], off offset:640
	v_lshl_add_u64 v[208:209], s[96:97], 0, v[208:209]
	v_lshl_add_u64 v[208:209], v[208:209], 0, v[206:207]
	s_waitcnt vmcnt(0)
	v_cvt_f32_f16_e32 v250, v212
	v_cvt_f32_f16_sdwa v251, v212 dst_sel:DWORD dst_unused:UNUSED_PAD src0_sel:WORD_1
	v_cvt_f32_f16_e32 v212, v213
	v_cvt_f32_f16_sdwa v213, v213 dst_sel:DWORD dst_unused:UNUSED_PAD src0_sel:WORD_1
	v_cvt_f32_f16_e32 v174, v214
	v_fmamk_f32 v128, v128, 0x3b2aaaab, v227
	s_nop 1
	v_rsq_f32_e32 v128, v128
	v_cvt_f32_f16_sdwa v175, v214 dst_sel:DWORD dst_unused:UNUSED_PAD src0_sel:WORD_1
	v_cvt_f32_f16_e32 v214, v215
	v_cvt_f32_f16_sdwa v215, v215 dst_sel:DWORD dst_unused:UNUSED_PAD src0_sel:WORD_1
	v_pk_mul_f32 v[124:125], v[124:125], v[128:129] op_sel_hi:[1,0]
	v_pk_mul_f32 v[126:127], v[126:127], v[128:129] op_sel_hi:[1,0]
	v_pk_mul_f32 v[176:177], v[120:121], v[128:129] op_sel_hi:[1,0]
	v_pk_mul_f32 v[122:123], v[122:123], v[128:129] op_sel_hi:[1,0]
	v_pk_fma_f32 v[120:121], v[136:137], v[126:127], v[212:213]
	v_pk_fma_f32 v[124:125], v[134:135], v[124:125], v[250:251]
	v_pk_fma_f32 v[122:123], v[132:133], v[122:123], v[214:215]
	v_pk_fma_f32 v[126:127], v[130:131], v[176:177], v[174:175]
	v_cvt_pk_f16_f32 v212, v124, v125
	v_cvt_pk_f16_f32 v213, v120, v121
	v_cvt_pk_f16_f32 v214, v126, v127
	v_cvt_pk_f16_f32 v215, v122, v123
	global_store_dwordx4 v[208:209], v[212:215], off
	s_nop 0
	v_lshl_add_u64 v[174:175], s[96:97], 0, v[246:247]
	v_lshl_add_u64 v[212:213], v[174:175], 0, v[206:207]
	v_cvt_f32_f16_e32 v174, v242
	v_cvt_f32_f16_sdwa v175, v242 dst_sel:DWORD dst_unused:UNUSED_PAD src0_sel:WORD_1
	v_cvt_f32_f16_e32 v176, v243
	v_cvt_f32_f16_sdwa v177, v243 dst_sel:DWORD dst_unused:UNUSED_PAD src0_sel:WORD_1
	v_cvt_f32_f16_e32 v214, v244
	v_cvt_f32_f16_e32 v242, v245
	v_cvt_f32_f16_sdwa v243, v245 dst_sel:DWORD dst_unused:UNUSED_PAD src0_sel:WORD_1
	v_fmamk_f32 v128, v163, 0x3b2aaaab, v227
	s_nop 1
	v_rsq_f32_e32 v128, v128
	v_cvt_f32_f16_sdwa v215, v244 dst_sel:DWORD dst_unused:UNUSED_PAD src0_sel:WORD_1
	v_pk_mul_f32 v[244:245], v[116:117], v[128:129] op_sel_hi:[1,0]
	v_pk_mul_f32 v[116:117], v[118:119], v[128:129] op_sel_hi:[1,0]
	v_pk_mul_f32 v[246:247], v[112:113], v[128:129] op_sel_hi:[1,0]
	v_pk_mul_f32 v[112:113], v[114:115], v[128:129] op_sel_hi:[1,0]
	v_pk_fma_f32 v[116:117], v[136:137], v[116:117], v[176:177]
	v_pk_fma_f32 v[118:119], v[134:135], v[244:245], v[174:175]
	v_pk_fma_f32 v[112:113], v[132:133], v[112:113], v[242:243]
	v_pk_fma_f32 v[114:115], v[130:131], v[246:247], v[214:215]
	v_cvt_pk_f16_f32 v242, v118, v119
	v_cvt_pk_f16_f32 v243, v116, v117
	v_cvt_pk_f16_f32 v244, v114, v115
	v_cvt_pk_f16_f32 v245, v112, v113
	global_store_dwordx4 v[212:213], v[242:245], off
	s_nop 0
	v_lshl_add_u64 v[174:175], s[96:97], 0, v[248:249]
	v_lshl_add_u64 v[214:215], v[174:175], 0, v[206:207]
	v_cvt_f32_f16_e32 v174, v158
	v_cvt_f32_f16_sdwa v175, v158 dst_sel:DWORD dst_unused:UNUSED_PAD src0_sel:WORD_1
	v_cvt_f32_f16_e32 v158, v159
	v_cvt_f32_f16_sdwa v159, v159 dst_sel:DWORD dst_unused:UNUSED_PAD src0_sel:WORD_1
	v_cvt_f32_f16_e32 v176, v160
	v_fmamk_f32 v128, v165, 0x3b2aaaab, v227
	s_nop 1
	v_rsq_f32_e32 v128, v128
; __device__ __forceinline__ unsigned pk_f16(float lo, float hi) { f32x2 v = {lo, hi}; f16x2_t h = __builtin_convertvector(v, f16x2_t); return __builtin_bit_cast(unsigned, h); }
; __device__ __forceinline__ f32x2 up_f16(unsigned w) { return __builtin_convertvector(__builtin_bit_cast(f16x2_t, w), f32x2); }
;     __device__ __forceinline__ void operator()(const f32x4 (&acc)[2][2][4][2], const Unit& u, int wr, int wc, int fr, int fq) const {
;     ...
;                 for (int m = 0; m < 4; ++m) { const size_t off = (size_t)(row0 + ai * HALF + m * 16) * 1024 + col0 + bj * HALF;
;                     float rc = 1.0f; if constexpr (GN) rc = rsqrtf(gss[2 * 32768 + row0 + ai * HALF + m * 16] * (1.0f / 384.0f) + 1e-6f);
;                     const u32x4 q = pq[ai][m];
;                     const f32x2 qa_ = up_f16(q.x), qb_ = up_f16(q.y), qc_ = up_f16(q.z), qd_ = up_f16(q.w);
;                     const f32x4 x0 = (f32x4){qa_[0], qa_[1], qb_[0], qb_[1]} + gv[0] * (acc[ai][bj][m][0] * rc),
;                                 x1 = (f32x4){qc_[0], qc_[1], qd_[0], qd_[1]} + gv[1] * (acc[ai][bj][m][1] * rc);
;                     { u32x4 wx; wx.x = pk_f16(x0[0], x0[1]); wx.y = pk_f16(x0[2], x0[3]); wx.z = pk_f16(x1[0], x1[1]); wx.w = pk_f16(x1[2], x1[3]); *(u32x4*)(out + off) = wx; }
	v_cvt_f32_f16_sdwa v177, v160 dst_sel:DWORD dst_unused:UNUSED_PAD src0_sel:WORD_1
	v_cvt_f32_f16_e32 v160, v161
	v_cvt_f32_f16_sdwa v161, v161 dst_sel:DWORD dst_unused:UNUSED_PAD src0_sel:WORD_1
	v_pk_mul_f32 v[242:243], v[108:109], v[128:129] op_sel_hi:[1,0]
	v_pk_mul_f32 v[108:109], v[110:111], v[128:129] op_sel_hi:[1,0]
	v_pk_mul_f32 v[244:245], v[104:105], v[128:129] op_sel_hi:[1,0]
	v_pk_mul_f32 v[104:105], v[106:107], v[128:129] op_sel_hi:[1,0]
	v_pk_fma_f32 v[108:109], v[136:137], v[108:109], v[158:159]
	v_pk_fma_f32 v[110:111], v[134:135], v[242:243], v[174:175]
	v_pk_fma_f32 v[104:105], v[132:133], v[104:105], v[160:161]
	v_pk_fma_f32 v[106:107], v[130:131], v[244:245], v[176:177]
	v_cvt_pk_f16_f32 v158, v110, v111
	v_cvt_pk_f16_f32 v159, v108, v109
	v_cvt_pk_f16_f32 v160, v106, v107
	v_cvt_pk_f16_f32 v161, v104, v105
	global_store_dwordx4 v[214:215], v[158:161], off
	s_nop 0
	v_cvt_f32_f16_e32 v174, v156
	v_cvt_f32_f16_e32 v160, v154
	v_cvt_f32_f16_sdwa v161, v154 dst_sel:DWORD dst_unused:UNUSED_PAD src0_sel:WORD_1
	v_cvt_f32_f16_e32 v154, v155
	v_cvt_f32_f16_sdwa v155, v155 dst_sel:DWORD dst_unused:UNUSED_PAD src0_sel:WORD_1
	v_lshl_add_u64 v[158:159], s[96:97], 0, v[224:225]
	v_lshl_add_u64 v[158:159], v[158:159], 0, v[206:207]
	v_fmamk_f32 v128, v167, 0x3b2aaaab, v227
	s_nop 1
	v_rsq_f32_e32 v128, v128
	v_cvt_f32_f16_sdwa v175, v156 dst_sel:DWORD dst_unused:UNUSED_PAD src0_sel:WORD_1
	v_cvt_f32_f16_e32 v156, v157
	v_cvt_f32_f16_sdwa v157, v157 dst_sel:DWORD dst_unused:UNUSED_PAD src0_sel:WORD_1
	v_pk_mul_f32 v[176:177], v[100:101], v[128:129] op_sel_hi:[1,0]
	v_pk_mul_f32 v[100:101], v[102:103], v[128:129] op_sel_hi:[1,0]
	v_pk_mul_f32 v[224:225], v[96:97], v[128:129] op_sel_hi:[1,0]
	v_pk_mul_f32 v[96:97], v[98:99], v[128:129] op_sel_hi:[1,0]
	v_pk_fma_f32 v[100:101], v[136:137], v[100:101], v[154:155]
	v_pk_fma_f32 v[102:103], v[134:135], v[176:177], v[160:161]
	v_pk_fma_f32 v[96:97], v[132:133], v[96:97], v[156:157]
	v_pk_fma_f32 v[98:99], v[130:131], v[224:225], v[174:175]
	v_cvt_pk_f16_f32 v154, v102, v103
	v_cvt_pk_f16_f32 v155, v100, v101
	v_cvt_pk_f16_f32 v156, v98, v99
	v_cvt_pk_f16_f32 v157, v96, v97
	global_store_dwordx4 v[158:159], v[154:157], off
	s_nop 0
	v_fmamk_f32 v128, v169, 0x3b2aaaab, v227
	v_lshl_add_u64 v[154:155], s[96:97], 0, v[218:219]
	v_lshl_add_u64 v[218:219], v[154:155], 0, v[206:207]
	v_rsq_f32_e32 v128, v128
	v_cvt_f32_f16_e32 v154, v150
	v_cvt_f32_f16_sdwa v155, v150 dst_sel:DWORD dst_unused:UNUSED_PAD src0_sel:WORD_1
	v_cvt_f32_f16_e32 v150, v151
	v_cvt_f32_f16_sdwa v151, v151 dst_sel:DWORD dst_unused:UNUSED_PAD src0_sel:WORD_1
	v_cvt_f32_f16_e32 v156, v152
	v_cvt_f32_f16_sdwa v157, v152 dst_sel:DWORD dst_unused:UNUSED_PAD src0_sel:WORD_1
	v_cvt_f32_f16_e32 v152, v153
	v_cvt_f32_f16_sdwa v153, v153 dst_sel:DWORD dst_unused:UNUSED_PAD src0_sel:WORD_1
	v_pk_mul_f32 v[160:161], v[92:93], v[128:129] op_sel_hi:[1,0]
	v_pk_mul_f32 v[92:93], v[94:95], v[128:129] op_sel_hi:[1,0]
	v_pk_mul_f32 v[174:175], v[88:89], v[128:129] op_sel_hi:[1,0]
	v_pk_mul_f32 v[88:89], v[90:91], v[128:129] op_sel_hi:[1,0]
	v_pk_fma_f32 v[92:93], v[136:137], v[92:93], v[150:151]
	v_pk_fma_f32 v[94:95], v[134:135], v[160:161], v[154:155]
	v_pk_fma_f32 v[88:89], v[132:133], v[88:89], v[152:153]
	v_pk_fma_f32 v[90:91], v[130:131], v[174:175], v[156:157]
	v_cvt_pk_f16_f32 v150, v94, v95
	v_cvt_pk_f16_f32 v151, v92, v93
	v_cvt_pk_f16_f32 v152, v90, v91
	v_cvt_pk_f16_f32 v153, v88, v89
	global_store_dwordx4 v[218:219], v[150:153], off
	s_nop 0
	v_cvt_f32_f16_e32 v154, v148
	v_lshl_add_u64 v[150:151], s[96:97], 0, v[220:221]
	v_lshl_add_u64 v[220:221], v[150:151], 0, v[206:207]
	v_cvt_f32_f16_e32 v152, v146
	v_cvt_f32_f16_sdwa v153, v146 dst_sel:DWORD dst_unused:UNUSED_PAD src0_sel:WORD_1
	v_cvt_f32_f16_e32 v146, v147
	v_cvt_f32_f16_sdwa v147, v147 dst_sel:DWORD dst_unused:UNUSED_PAD src0_sel:WORD_1
	v_cvt_f32_f16_sdwa v155, v148 dst_sel:DWORD dst_unused:UNUSED_PAD src0_sel:WORD_1
	v_cvt_f32_f16_e32 v148, v149
	v_cvt_f32_f16_sdwa v149, v149 dst_sel:DWORD dst_unused:UNUSED_PAD src0_sel:WORD_1
	v_fmamk_f32 v128, v171, 0x3b2aaaab, v227
	s_nop 1
	v_rsq_f32_e32 v128, v128
	s_nop 0
	v_pk_mul_f32 v[84:85], v[84:85], v[128:129] op_sel_hi:[1,0]
	v_pk_mul_f32 v[86:87], v[86:87], v[128:129] op_sel_hi:[1,0]
	v_pk_mul_f32 v[80:81], v[80:81], v[128:129] op_sel_hi:[1,0]
	v_pk_mul_f32 v[82:83], v[82:83], v[128:129] op_sel_hi:[1,0]
	v_pk_fma_f32 v[150:151], v[136:137], v[86:87], v[146:147]
	v_pk_fma_f32 v[152:153], v[134:135], v[84:85], v[152:153]
	v_pk_fma_f32 v[146:147], v[132:133], v[82:83], v[148:149]
	v_pk_fma_f32 v[148:149], v[130:131], v[80:81], v[154:155]
	v_cvt_pk_f16_f32 v80, v152, v153
	v_cvt_pk_f16_f32 v81, v150, v151
	v_cvt_pk_f16_f32 v82, v148, v149
	v_cvt_pk_f16_f32 v83, v146, v147
	global_store_dwordx4 v[220:221], v[80:83], off
	s_nop 0
	v_cvt_f32_f16_e32 v84, v144
	v_lshl_add_u64 v[80:81], s[96:97], 0, v[222:223]
	v_lshl_add_u64 v[222:223], v[80:81], 0, v[206:207]
	v_cvt_f32_f16_e32 v80, v142
	v_cvt_f32_f16_sdwa v81, v142 dst_sel:DWORD dst_unused:UNUSED_PAD src0_sel:WORD_1
	v_cvt_f32_f16_e32 v82, v143
	v_cvt_f32_f16_sdwa v83, v143 dst_sel:DWORD dst_unused:UNUSED_PAD src0_sel:WORD_1
	v_cvt_f32_f16_sdwa v87, v145 dst_sel:DWORD dst_unused:UNUSED_PAD src0_sel:WORD_1
	v_fmamk_f32 v85, v173, 0x3b2aaaab, v227
	s_nop 1
	v_rsq_f32_e32 v128, v85
	v_cvt_f32_f16_sdwa v85, v144 dst_sel:DWORD dst_unused:UNUSED_PAD src0_sel:WORD_1
	v_cvt_f32_f16_e32 v86, v145
	v_pk_mul_f32 v[76:77], v[76:77], v[128:129] op_sel_hi:[1,0]
	v_pk_mul_f32 v[78:79], v[78:79], v[128:129] op_sel_hi:[1,0]
	v_pk_mul_f32 v[72:73], v[72:73], v[128:129] op_sel_hi:[1,0]
	v_pk_mul_f32 v[74:75], v[74:75], v[128:129] op_sel_hi:[1,0]
	v_pk_fma_f32 v[154:155], v[136:137], v[78:79], v[82:83]
	v_pk_fma_f32 v[156:157], v[134:135], v[76:77], v[80:81]
	v_pk_fma_f32 v[142:143], v[132:133], v[74:75], v[86:87]
	v_pk_fma_f32 v[144:145], v[130:131], v[72:73], v[84:85]
	v_cvt_pk_f16_f32 v72, v156, v157
	v_cvt_pk_f16_f32 v73, v154, v155
	v_cvt_pk_f16_f32 v74, v144, v145
	v_cvt_pk_f16_f32 v75, v142, v143
	global_store_dwordx4 v[222:223], v[72:75], off
	global_load_dword v77, v[188:189], off offset:704
	v_cvt_f32_f16_e32 v76, v140
	v_lshl_add_u64 v[72:73], s[96:97], 0, v[216:217]
	v_lshl_add_u64 v[160:161], v[72:73], 0, v[206:207]
	v_cvt_f32_f16_e32 v72, v138
	v_cvt_f32_f16_sdwa v73, v138 dst_sel:DWORD dst_unused:UNUSED_PAD src0_sel:WORD_1
	v_cvt_f32_f16_e32 v74, v139
	v_cvt_f32_f16_sdwa v75, v139 dst_sel:DWORD dst_unused:UNUSED_PAD src0_sel:WORD_1
	v_cvt_f32_f16_sdwa v79, v141 dst_sel:DWORD dst_unused:UNUSED_PAD src0_sel:WORD_1
	s_waitcnt vmcnt(0)
; __device__ __forceinline__ unsigned pk_f16(float lo, float hi) { f32x2 v = {lo, hi}; f16x2_t h = __builtin_convertvector(v, f16x2_t); return __builtin_bit_cast(unsigned, h); }
; __device__ __forceinline__ f32x2 up_f16(unsigned w) { return __builtin_convertvector(__builtin_bit_cast(f16x2_t, w), f32x2); }
;     __device__ __forceinline__ void operator()(const f32x4 (&acc)[2][2][4][2], const Unit& u, int wr, int wc, int fr, int fq) const {
;     ...
;                 for (int m = 0; m < 4; ++m) { const size_t off = (size_t)(row0 + ai * HALF + m * 16) * 1024 + col0 + bj * HALF;
;                     float rc = 1.0f; if constexpr (GN) rc = rsqrtf(gss[2 * 32768 + row0 + ai * HALF + m * 16] * (1.0f / 384.0f) + 1e-6f);
;                     const u32x4 q = pq[ai][m];
;                     const f32x2 qa_ = up_f16(q.x), qb_ = up_f16(q.y), qc_ = up_f16(q.z), qd_ = up_f16(q.w);
;                     const f32x4 x0 = (f32x4){qa_[0], qa_[1], qb_[0], qb_[1]} + gv[0] * (acc[ai][bj][m][0] * rc),
;                                 x1 = (f32x4){qc_[0], qc_[1], qd_[0], qd_[1]} + gv[1] * (acc[ai][bj][m][1] * rc);
;                     { u32x4 wx; wx.x = pk_f16(x0[0], x0[1]); wx.y = pk_f16(x0[2], x0[3]); wx.z = pk_f16(x1[0], x1[1]); wx.w = pk_f16(x1[2], x1[3]); *(u32x4*)(out + off) = wx; }
;                     ss[ai][m] += ((x0[0] * x0[0] + x0[1] * x0[1]) + (x0[2] * x0[2] + x0[3] * x0[3])) + ((x1[0] * x1[0] + x1[1] * x1[1]) + (x1[2] * x1[2] + x1[3] * x1[3]));
	v_fmamk_f32 v77, v77, 0x3b2aaaab, v227
	s_nop 1
	v_rsq_f32_e32 v80, v77
	v_cvt_f32_f16_sdwa v77, v140 dst_sel:DWORD dst_unused:UNUSED_PAD src0_sel:WORD_1
	v_cvt_f32_f16_e32 v78, v141
	v_pk_mul_f32 v[68:69], v[68:69], v[80:81] op_sel_hi:[1,0]
	v_pk_mul_f32 v[70:71], v[70:71], v[80:81] op_sel_hi:[1,0]
	v_pk_mul_f32 v[64:65], v[64:65], v[80:81] op_sel_hi:[1,0]
	v_pk_mul_f32 v[66:67], v[66:67], v[80:81] op_sel_hi:[1,0]
	v_pk_fma_f32 v[136:137], v[136:137], v[70:71], v[74:75]
	v_pk_fma_f32 v[134:135], v[134:135], v[68:69], v[72:73]
	v_pk_fma_f32 v[132:133], v[132:133], v[66:67], v[78:79]
	v_pk_fma_f32 v[130:131], v[130:131], v[64:65], v[76:77]
	v_cvt_pk_f16_f32 v64, v134, v135
	v_cvt_pk_f16_f32 v65, v136, v137
	v_cvt_pk_f16_f32 v66, v130, v131
	v_cvt_pk_f16_f32 v67, v132, v133
	global_store_dwordx4 v[160:161], v[64:67], off
	global_load_dwordx4 v[64:67], v[190:191], off offset:528
	global_load_dwordx4 v[68:71], v[190:191], off offset:512
	global_load_dwordx4 v[138:141], v[192:193], off offset:256
	s_nop 0
	global_load_dwordx4 v[190:193], v[194:195], off offset:256
	s_nop 0
	global_load_dwordx4 v[194:197], v[196:197], off offset:256
	s_nop 0
	global_load_dwordx4 v[242:245], v[198:199], off offset:256
	global_load_dwordx4 v[84:87], v[200:201], off offset:256
	global_load_dwordx4 v[80:83], v[202:203], off offset:256
	global_load_dwordx4 v[76:79], v[204:205], off offset:256
	global_load_dwordx4 v[72:75], v[210:211], off offset:256
	global_load_dword v128, v[188:189], off
	s_waitcnt vmcnt(8)
	v_cvt_f32_f16_e32 v174, v138
	v_cvt_f32_f16_sdwa v175, v138 dst_sel:DWORD dst_unused:UNUSED_PAD src0_sel:WORD_1
	v_cvt_f32_f16_e32 v138, v139
	v_cvt_f32_f16_sdwa v139, v139 dst_sel:DWORD dst_unused:UNUSED_PAD src0_sel:WORD_1
	v_cvt_f32_f16_e32 v176, v140
	s_waitcnt vmcnt(0)
	v_fmamk_f32 v128, v128, 0x3b2aaaab, v227
	s_nop 1
	v_rsq_f32_e32 v128, v128
	v_cvt_f32_f16_sdwa v177, v140 dst_sel:DWORD dst_unused:UNUSED_PAD src0_sel:WORD_1
	v_cvt_f32_f16_e32 v140, v141
	v_cvt_f32_f16_sdwa v141, v141 dst_sel:DWORD dst_unused:UNUSED_PAD src0_sel:WORD_1
	v_pk_mul_f32 v[60:61], v[60:61], v[128:129] op_sel_hi:[1,0]
	v_pk_mul_f32 v[62:63], v[62:63], v[128:129] op_sel_hi:[1,0]
	v_pk_mul_f32 v[198:199], v[56:57], v[128:129] op_sel_hi:[1,0]
	v_pk_mul_f32 v[200:201], v[58:59], v[128:129] op_sel_hi:[1,0]
	v_pk_fma_f32 v[56:57], v[70:71], v[62:63], v[138:139]
	v_pk_fma_f32 v[58:59], v[68:69], v[60:61], v[174:175]
	v_pk_fma_f32 v[60:61], v[66:67], v[200:201], v[140:141]
	v_pk_fma_f32 v[62:63], v[64:65], v[198:199], v[176:177]
	v_cvt_pk_f16_f32 v138, v58, v59
	v_cvt_pk_f16_f32 v139, v56, v57
	v_cvt_pk_f16_f32 v140, v62, v63
	v_cvt_pk_f16_f32 v141, v60, v61
	global_store_dwordx4 v[208:209], v[138:141], off offset:256
	s_nop 0
	v_cvt_f32_f16_e32 v174, v192
	v_cvt_f32_f16_e32 v138, v190
	v_cvt_f32_f16_sdwa v139, v190 dst_sel:DWORD dst_unused:UNUSED_PAD src0_sel:WORD_1
	v_cvt_f32_f16_e32 v140, v191
	v_cvt_f32_f16_sdwa v141, v191 dst_sel:DWORD dst_unused:UNUSED_PAD src0_sel:WORD_1
	v_cvt_f32_f16_e32 v176, v193
	v_cvt_f32_f16_sdwa v177, v193 dst_sel:DWORD dst_unused:UNUSED_PAD src0_sel:WORD_1
	v_mul_f32_e32 v59, v59, v59
	v_mul_f32_e32 v57, v57, v57
	v_mul_f32_e32 v63, v63, v63
	v_mul_f32_e32 v61, v61, v61
	v_fmac_f32_e32 v59, v58, v58
	v_fmac_f32_e32 v57, v56, v56
	v_fmac_f32_e32 v63, v62, v62
	v_fmac_f32_e32 v61, v60, v60
	v_add_f32_e32 v56, v59, v57
	v_add_f32_e32 v57, v63, v61
	v_add_f32_e32 v56, v56, v57
	v_cvt_f32_f16_e32 v60, v75
	v_cvt_f32_f16_sdwa v61, v75 dst_sel:DWORD dst_unused:UNUSED_PAD src0_sel:WORD_1
	v_fmamk_f32 v128, v163, 0x3b2aaaab, v227
	s_nop 1
	v_rsq_f32_e32 v128, v128
	v_cvt_f32_f16_sdwa v175, v192 dst_sel:DWORD dst_unused:UNUSED_PAD src0_sel:WORD_1
	v_pk_mul_f32 v[190:191], v[52:53], v[128:129] op_sel_hi:[1,0]
	v_pk_mul_f32 v[52:53], v[54:55], v[128:129] op_sel_hi:[1,0]
	v_pk_mul_f32 v[192:193], v[48:49], v[128:129] op_sel_hi:[1,0]
	v_pk_mul_f32 v[48:49], v[50:51], v[128:129] op_sel_hi:[1,0]
	v_pk_fma_f32 v[52:53], v[70:71], v[52:53], v[140:141]
	v_pk_fma_f32 v[54:55], v[68:69], v[190:191], v[138:139]
	v_pk_fma_f32 v[48:49], v[66:67], v[48:49], v[176:177]
	v_pk_fma_f32 v[50:51], v[64:65], v[192:193], v[174:175]
	v_cvt_pk_f16_f32 v138, v54, v55
	v_cvt_pk_f16_f32 v139, v52, v53
	v_cvt_pk_f16_f32 v140, v50, v51
	v_cvt_pk_f16_f32 v141, v48, v49
	global_store_dwordx4 v[212:213], v[138:141], off offset:256
	s_nop 0
	v_cvt_f32_f16_e32 v174, v196
	v_cvt_f32_f16_e32 v138, v194
	v_cvt_f32_f16_sdwa v139, v194 dst_sel:DWORD dst_unused:UNUSED_PAD src0_sel:WORD_1
	v_cvt_f32_f16_e32 v140, v195
	v_cvt_f32_f16_sdwa v141, v195 dst_sel:DWORD dst_unused:UNUSED_PAD src0_sel:WORD_1
	v_cvt_f32_f16_e32 v176, v197
	v_cvt_f32_f16_sdwa v177, v197 dst_sel:DWORD dst_unused:UNUSED_PAD src0_sel:WORD_1
	v_fmamk_f32 v128, v165, 0x3b2aaaab, v227
	s_nop 1
	v_rsq_f32_e32 v128, v128
	v_cvt_f32_f16_sdwa v175, v196 dst_sel:DWORD dst_unused:UNUSED_PAD src0_sel:WORD_1
	v_pk_mul_f32 v[190:191], v[44:45], v[128:129] op_sel_hi:[1,0]
	v_pk_mul_f32 v[44:45], v[46:47], v[128:129] op_sel_hi:[1,0]
	v_pk_mul_f32 v[192:193], v[40:41], v[128:129] op_sel_hi:[1,0]
	v_pk_mul_f32 v[40:41], v[42:43], v[128:129] op_sel_hi:[1,0]
	v_pk_fma_f32 v[44:45], v[70:71], v[44:45], v[140:141]
	v_pk_fma_f32 v[46:47], v[68:69], v[190:191], v[138:139]
	v_pk_fma_f32 v[40:41], v[66:67], v[40:41], v[176:177]
	v_pk_fma_f32 v[42:43], v[64:65], v[192:193], v[174:175]
	v_cvt_pk_f16_f32 v138, v46, v47
	v_cvt_pk_f16_f32 v139, v44, v45
	v_cvt_pk_f16_f32 v140, v42, v43
	v_cvt_pk_f16_f32 v141, v40, v41
	global_store_dwordx4 v[214:215], v[138:141], off offset:256
	s_nop 0
	v_cvt_f32_f16_e32 v174, v244
	v_cvt_f32_f16_e32 v138, v242
; __device__ __forceinline__ unsigned pk_f16(float lo, float hi) { f32x2 v = {lo, hi}; f16x2_t h = __builtin_convertvector(v, f16x2_t); return __builtin_bit_cast(unsigned, h); }
; __device__ __forceinline__ f32x2 up_f16(unsigned w) { return __builtin_convertvector(__builtin_bit_cast(f16x2_t, w), f32x2); }
;     __device__ __forceinline__ void operator()(const f32x4 (&acc)[2][2][4][2], const Unit& u, int wr, int wc, int fr, int fq) const {
;     ...
;                 for (int m = 0; m < 4; ++m) { const size_t off = (size_t)(row0 + ai * HALF + m * 16) * 1024 + col0 + bj * HALF;
;                     float rc = 1.0f; if constexpr (GN) rc = rsqrtf(gss[2 * 32768 + row0 + ai * HALF + m * 16] * (1.0f / 384.0f) + 1e-6f);
;                     const u32x4 q = pq[ai][m];
;                     const f32x2 qa_ = up_f16(q.x), qb_ = up_f16(q.y), qc_ = up_f16(q.z), qd_ = up_f16(q.w);
;                     const f32x4 x0 = (f32x4){qa_[0], qa_[1], qb_[0], qb_[1]} + gv[0] * (acc[ai][bj][m][0] * rc),
;                                 x1 = (f32x4){qc_[0], qc_[1], qd_[0], qd_[1]} + gv[1] * (acc[ai][bj][m][1] * rc);
;                     { u32x4 wx; wx.x = pk_f16(x0[0], x0[1]); wx.y = pk_f16(x0[2], x0[3]); wx.z = pk_f16(x1[0], x1[1]); wx.w = pk_f16(x1[2], x1[3]); *(u32x4*)(out + off) = wx; }
;                     ss[ai][m] += ((x0[0] * x0[0] + x0[1] * x0[1]) + (x0[2] * x0[2] + x0[3] * x0[3])) + ((x1[0] * x1[0] + x1[1] * x1[1]) + (x1[2] * x1[2] + x1[3] * x1[3]));
;     ...
;             for (int m = 0; m < 4; ++m) { float t = ss[ai][m]; t += __shfl_xor(t, 16); t += __shfl_xor(t, 32);
;                 if (fq == 0) atomicAdd(rowss + row0 + ai * HALF + m * 16, t); }
	v_cvt_f32_f16_sdwa v139, v242 dst_sel:DWORD dst_unused:UNUSED_PAD src0_sel:WORD_1
	v_cvt_f32_f16_e32 v140, v243
	v_cvt_f32_f16_sdwa v141, v243 dst_sel:DWORD dst_unused:UNUSED_PAD src0_sel:WORD_1
	v_cvt_f32_f16_e32 v176, v245
	v_cvt_f32_f16_sdwa v177, v245 dst_sel:DWORD dst_unused:UNUSED_PAD src0_sel:WORD_1
	v_fmamk_f32 v128, v167, 0x3b2aaaab, v227
	s_nop 1
	v_rsq_f32_e32 v128, v128
	v_cvt_f32_f16_sdwa v175, v244 dst_sel:DWORD dst_unused:UNUSED_PAD src0_sel:WORD_1
	v_pk_mul_f32 v[190:191], v[36:37], v[128:129] op_sel_hi:[1,0]
	v_pk_mul_f32 v[36:37], v[38:39], v[128:129] op_sel_hi:[1,0]
	v_pk_mul_f32 v[192:193], v[32:33], v[128:129] op_sel_hi:[1,0]
	v_pk_mul_f32 v[32:33], v[34:35], v[128:129] op_sel_hi:[1,0]
	v_pk_fma_f32 v[36:37], v[70:71], v[36:37], v[140:141]
	v_pk_fma_f32 v[38:39], v[68:69], v[190:191], v[138:139]
	v_pk_fma_f32 v[32:33], v[66:67], v[32:33], v[176:177]
	v_pk_fma_f32 v[34:35], v[64:65], v[192:193], v[174:175]
	v_cvt_pk_f16_f32 v138, v38, v39
	v_cvt_pk_f16_f32 v139, v36, v37
	v_cvt_pk_f16_f32 v140, v34, v35
	v_cvt_pk_f16_f32 v141, v32, v33
	global_store_dwordx4 v[158:159], v[138:141], off offset:256
	s_nop 0
	v_fmamk_f32 v128, v169, 0x3b2aaaab, v227
	v_cvt_f32_f16_e32 v138, v84
	v_cvt_f32_f16_sdwa v139, v84 dst_sel:DWORD dst_unused:UNUSED_PAD src0_sel:WORD_1
	v_rsq_f32_e32 v128, v128
	v_cvt_f32_f16_e32 v84, v85
	v_cvt_f32_f16_sdwa v85, v85 dst_sel:DWORD dst_unused:UNUSED_PAD src0_sel:WORD_1
	v_cvt_f32_f16_e32 v140, v86
	v_cvt_f32_f16_sdwa v141, v86 dst_sel:DWORD dst_unused:UNUSED_PAD src0_sel:WORD_1
	v_cvt_f32_f16_e32 v86, v87
	v_cvt_f32_f16_sdwa v87, v87 dst_sel:DWORD dst_unused:UNUSED_PAD src0_sel:WORD_1
	v_pk_mul_f32 v[158:159], v[28:29], v[128:129] op_sel_hi:[1,0]
	v_pk_mul_f32 v[28:29], v[30:31], v[128:129] op_sel_hi:[1,0]
	v_pk_mul_f32 v[174:175], v[24:25], v[128:129] op_sel_hi:[1,0]
	v_pk_mul_f32 v[24:25], v[26:27], v[128:129] op_sel_hi:[1,0]
	v_pk_fma_f32 v[28:29], v[70:71], v[28:29], v[84:85]
	v_pk_fma_f32 v[30:31], v[68:69], v[158:159], v[138:139]
	v_pk_fma_f32 v[24:25], v[66:67], v[24:25], v[86:87]
	v_pk_fma_f32 v[26:27], v[64:65], v[174:175], v[140:141]
	v_cvt_pk_f16_f32 v84, v30, v31
	v_cvt_pk_f16_f32 v85, v28, v29
	v_cvt_pk_f16_f32 v86, v26, v27
	v_cvt_pk_f16_f32 v87, v24, v25
	global_store_dwordx4 v[218:219], v[84:87], off offset:256
	s_nop 0
	s_nop 0
	v_cvt_f32_f16_e32 v84, v80
	v_cvt_f32_f16_sdwa v85, v80 dst_sel:DWORD dst_unused:UNUSED_PAD src0_sel:WORD_1
	v_cvt_f32_f16_e32 v80, v81
	v_cvt_f32_f16_sdwa v81, v81 dst_sel:DWORD dst_unused:UNUSED_PAD src0_sel:WORD_1
	v_cvt_f32_f16_e32 v86, v82
	v_fmamk_f32 v87, v171, 0x3b2aaaab, v227
	s_nop 1
	v_rsq_f32_e32 v128, v87
	v_cvt_f32_f16_sdwa v87, v82 dst_sel:DWORD dst_unused:UNUSED_PAD src0_sel:WORD_1
	v_cvt_f32_f16_e32 v82, v83
	v_cvt_f32_f16_sdwa v83, v83 dst_sel:DWORD dst_unused:UNUSED_PAD src0_sel:WORD_1
	v_pk_mul_f32 v[138:139], v[20:21], v[128:129] op_sel_hi:[1,0]
	v_pk_mul_f32 v[20:21], v[22:23], v[128:129] op_sel_hi:[1,0]
	v_pk_mul_f32 v[140:141], v[16:17], v[128:129] op_sel_hi:[1,0]
	v_pk_mul_f32 v[16:17], v[18:19], v[128:129] op_sel_hi:[1,0]
	v_pk_fma_f32 v[20:21], v[70:71], v[20:21], v[80:81]
	v_pk_fma_f32 v[22:23], v[68:69], v[138:139], v[84:85]
	v_pk_fma_f32 v[16:17], v[66:67], v[16:17], v[82:83]
	v_pk_fma_f32 v[18:19], v[64:65], v[140:141], v[86:87]
	v_cvt_pk_f16_f32 v80, v22, v23
	v_cvt_pk_f16_f32 v81, v20, v21
	v_cvt_pk_f16_f32 v82, v18, v19
	v_cvt_pk_f16_f32 v83, v16, v17
	global_store_dwordx4 v[220:221], v[80:83], off offset:256
	s_nop 0
	s_nop 0
	v_cvt_f32_f16_e32 v80, v76
	v_cvt_f32_f16_sdwa v81, v76 dst_sel:DWORD dst_unused:UNUSED_PAD src0_sel:WORD_1
	v_cvt_f32_f16_e32 v76, v77
	v_cvt_f32_f16_sdwa v77, v77 dst_sel:DWORD dst_unused:UNUSED_PAD src0_sel:WORD_1
	v_cvt_f32_f16_e32 v82, v78
	v_fmamk_f32 v83, v173, 0x3b2aaaab, v227
	v_mov_b32_e32 v163, v129
	v_mov_b32_e32 v165, v129
	v_mov_b32_e32 v167, v129
	v_mov_b32_e32 v169, v129
	v_mov_b32_e32 v171, v129
	v_mov_b32_e32 v173, v129
	s_nop 1
	v_rsq_f32_e32 v84, v83
	v_cvt_f32_f16_sdwa v83, v78 dst_sel:DWORD dst_unused:UNUSED_PAD src0_sel:WORD_1
	v_cvt_f32_f16_e32 v78, v79
	v_cvt_f32_f16_sdwa v79, v79 dst_sel:DWORD dst_unused:UNUSED_PAD src0_sel:WORD_1
	v_pk_mul_f32 v[86:87], v[12:13], v[84:85] op_sel_hi:[1,0]
	v_pk_mul_f32 v[12:13], v[14:15], v[84:85] op_sel_hi:[1,0]
	v_pk_mul_f32 v[138:139], v[8:9], v[84:85] op_sel_hi:[1,0]
	v_pk_mul_f32 v[8:9], v[10:11], v[84:85] op_sel_hi:[1,0]
	v_pk_fma_f32 v[12:13], v[70:71], v[12:13], v[76:77]
	v_pk_fma_f32 v[14:15], v[68:69], v[86:87], v[80:81]
	v_pk_fma_f32 v[8:9], v[66:67], v[8:9], v[78:79]
	v_pk_fma_f32 v[10:11], v[64:65], v[138:139], v[82:83]
	v_cvt_pk_f16_f32 v76, v14, v15
	v_cvt_pk_f16_f32 v77, v12, v13
	v_cvt_pk_f16_f32 v78, v10, v11
	v_cvt_pk_f16_f32 v79, v8, v9
	global_store_dwordx4 v[222:223], v[76:79], off offset:256
	global_load_dword v82, v[188:189], off offset:704
	v_mul_f32_e32 v80, v127, v127
	v_and_b32_e32 v77, 64, v230
	v_xor_b32_e32 v76, 16, v230
	v_add_u32_e32 v77, 64, v77
	v_xor_b32_e32 v78, 32, v230
	v_cmp_lt_i32_e32 vcc, v76, v77
	v_mul_f32_e32 v79, v121, v121
	v_mul_f32_e32 v81, v123, v123
	v_cndmask_b32_e32 v76, v230, v76, vcc
	v_cmp_lt_i32_e32 vcc, v78, v77
	v_lshlrev_b32_e32 v77, 2, v76
	v_fmac_f32_e32 v79, v120, v120
	v_cndmask_b32_e32 v78, v230, v78, vcc
	v_lshlrev_b32_e32 v76, 2, v78
	v_mul_f32_e32 v78, v125, v125
	v_fmac_f32_e32 v78, v124, v124
	v_fmac_f32_e32 v80, v126, v126
	v_fmac_f32_e32 v81, v122, v122
	v_add_f32_e32 v78, v78, v79
	v_add_f32_e32 v79, v80, v81
	v_add_f32_e32 v83, v78, v79
	v_add_f32_e32 v56, v83, v56
	ds_bpermute_b32 v57, v77, v56
	v_cvt_f32_f16_e32 v78, v72
	v_cvt_f32_f16_sdwa v79, v72 dst_sel:DWORD dst_unused:UNUSED_PAD src0_sel:WORD_1
	v_cvt_f32_f16_e32 v72, v73
	v_cvt_f32_f16_sdwa v73, v73 dst_sel:DWORD dst_unused:UNUSED_PAD src0_sel:WORD_1
	v_cvt_f32_f16_e32 v80, v74
	v_cvt_f32_f16_sdwa v81, v74 dst_sel:DWORD dst_unused:UNUSED_PAD src0_sel:WORD_1
	s_waitcnt vmcnt(0)
	v_fmamk_f32 v58, v82, 0x3b2aaaab, v227
	s_nop 1
	v_rsq_f32_e32 v59, v58
	s_waitcnt lgkmcnt(0)
	v_add_f32_e32 v58, v56, v57
	v_mov_b32_e32 v56, v59
	v_pk_mul_f32 v[4:5], v[4:5], v[56:57] op_sel_hi:[1,0]
	v_pk_mul_f32 v[6:7], v[6:7], v[56:57] op_sel_hi:[1,0]
	v_pk_mul_f32 v[0:1], v[0:1], v[56:57] op_sel_hi:[1,0]
	v_pk_mul_f32 v[2:3], v[2:3], v[56:57] op_sel_hi:[1,0]
	v_pk_fma_f32 v[6:7], v[70:71], v[6:7], v[72:73]
	v_pk_fma_f32 v[56:57], v[68:69], v[4:5], v[78:79]
	v_pk_fma_f32 v[2:3], v[66:67], v[2:3], v[60:61]
	v_pk_fma_f32 v[4:5], v[64:65], v[0:1], v[80:81]
	v_cvt_pk_f16_f32 v60, v56, v57
	v_cvt_pk_f16_f32 v61, v6, v7
	v_cvt_pk_f16_f32 v62, v4, v5
	v_cvt_pk_f16_f32 v63, v2, v3
	ds_bpermute_b32 v59, v76, v58
	global_store_dwordx4 v[160:161], v[60:63], off offset:256
	v_lshl_add_u64 v[0:1], v[186:187], 2, s[46:47]
	s_and_saveexec_b64 s[0:1], s[40:41]
	s_cbranch_execz .LBB0_808
	s_waitcnt lgkmcnt(0)
	v_add_f32_e32 v58, v58, v59
	global_atomic_add_f32 v[0:1], v58, off
